# DA loop: no LDS drain before the tile's first barrier or at the back edge (loop-carried counted lgkmcnt waits)
# baseline (speedup 1.0000x reference)
; __device__ void da_unit(char* lds, const Params& p, int layer, int unit) {
;     ...
;         DA_FAST_HALF(Bs, slope2, 0)
;         if (it + 1 < NT) {
; #pragma unroll
;             for (int j = 0; j < 4; ++j) *(u32x4*)(nK + (kr_ + 32 * j) * DA_KP + kc_ * 16) = rk[j];
; #pragma unroll
;             for (int j = 0; j < 4; ++j) rk[j] = *(const u32x4*)(Vg + (size_t)tn * 16384 + j * 4096);
;         }
;         DA_FAST_HALF(Bs, slope2, 1)
;     ...
;         if (it + 1 < NT) {
; #pragma unroll
;             for (int j = 0; j < 4; ++j) *(u32x4*)(nK + DA_KBYTES + (j >> 1) * DA_VSUB + (vr_ + 64 * (j & 1)) * DA_VP + vc_ * 16) = rk[j];
;         }
;         __syncthreads();
.Lda_noflip:
	s_add_i32 s0, s14, s4
	s_sub_i32 s1, 15, s4
	s_cmp_lt_u32 s4, s9
	s_cselect_b32 s10, s0, s1
	s_lshl_b32 s11, s10, 7
	s_add_i32 s16, s4, 1
	s_add_i32 s0, s14, s16
	s_sub_i32 s1, 15, s16
	s_cmp_lt_u32 s16, s9
	s_cselect_b32 s0, s0, s1
	s_add_i32 s16, s4, 2
	s_add_i32 s3, s14, s16
	s_sub_i32 s1, 15, s16
	s_cmp_lt_u32 s16, s9
	s_cselect_b32 s3, s3, s1
	s_bitcmp1_b32 s4, 0
	s_cselect_b32 s17, 0x11800, 0
	s_sub_i32 s5, 0x11800, s17
	s_add_i32 s1, s17, s8
	s_add_i32 s2, s17, 0x8800
	v_add3_u32 v234, s1, v186, v152
	v_add3_u32 v235, s2, v152, v154
	s_add_i32 s1, s5, s8
	s_add_i32 s2, s5, 0x8800
	v_add3_u32 v236, s1, v186, v152
	v_add3_u32 v178, s2, v152, v154
	v_cvt_f32_u32_e32 v242, s11
	v_add_f32_e32 v242, v185, v242
	v_fma_f32 v239, v242, v250, v169
	v_fma_f32 v253, v242, -v250, v64
	v_sub_f32_e32 v241, v169, v253
	v_mfma_f32_32x32x16_bf16 v[98:113], v[210:213], v[114:117], v[66:81]
	ds_read_b128 v[210:213], v234 offset:17408
	v_sub_f32_e32 v82, v82, v239
	v_sub_f32_e32 v83, v83, v239
	v_sub_f32_e32 v84, v84, v239
	v_sub_f32_e32 v85, v85, v239
	v_exp_f32_e32 v82, v82
	s_waitcnt lgkmcnt(6)
	v_mfma_f32_32x32x16_bf16 v[48:63], v[226:229], v[202:205], v[48:63]
	ds_read_b128 v[226:229], v178 offset:18528
	v_exp_f32_e32 v83, v83
	v_exp_f32_e32 v84, v84
	v_exp_f32_e32 v85, v85
	s_waitcnt lgkmcnt(6)
	v_mfma_f32_32x32x16_bf16 v[32:47], v[230:233], v[202:205], v[32:47]
	ds_read_b128 v[230:233], v178 offset:23136
	v_add_f32_e32 v191, v191, v82
	v_add_f32_e32 v192, v192, v83
	v_cvt_pk_bf16_f32 v194, v82, v83
	v_add_f32_e32 v191, v191, v84
	v_add_f32_e32 v192, v192, v85
	v_cvt_pk_bf16_f32 v195, v84, v85
	v_mfma_f32_32x32x16_bf16 v[98:113], v[214:217], v[118:121], v[98:113]
	ds_read_b128 v[214:217], v234 offset:17440
	v_sub_f32_e32 v86, v86, v239
	v_sub_f32_e32 v87, v87, v239
	v_sub_f32_e32 v88, v88, v239
	v_sub_f32_e32 v89, v89, v239
	v_exp_f32_e32 v86, v86
	s_waitcnt lgkmcnt(6)
	v_mfma_f32_32x32x16_bf16 v[16:31], v[174:177], v[202:205], v[16:31]
	ds_read_b128 v[174:177], v178 offset:27744
	v_exp_f32_e32 v87, v87
	v_exp_f32_e32 v88, v88
	v_exp_f32_e32 v89, v89
	s_waitcnt lgkmcnt(6)
	v_mfma_f32_32x32x16_bf16 v[0:15], v[246:249], v[202:205], v[0:15]
	ds_read_b128 v[246:249], v178 offset:32352
	v_add_f32_e32 v191, v191, v86
	v_add_f32_e32 v192, v192, v87
	v_cvt_pk_bf16_f32 v196, v86, v87
	v_add_f32_e32 v191, v191, v88
	v_add_f32_e32 v192, v192, v89
	v_cvt_pk_bf16_f32 v197, v88, v89
	v_mfma_f32_32x32x16_bf16 v[98:113], v[218:221], v[122:125], v[98:113]
	ds_read_b128 v[218:221], v234 offset:17472
	v_sub_f32_e32 v90, v90, v239
	v_sub_f32_e32 v91, v91, v239
	v_sub_f32_e32 v92, v92, v239
	v_sub_f32_e32 v93, v93, v239
	v_exp_f32_e32 v90, v90
	s_waitcnt lgkmcnt(5)
	v_mfma_f32_32x32x16_bf16 v[48:63], v[226:229], v[206:209], v[48:63]
	ds_read_b128 v[226:229], v235 offset:0
	v_exp_f32_e32 v91, v91
	v_exp_f32_e32 v92, v92
	v_exp_f32_e32 v93, v93
	s_waitcnt lgkmcnt(5)
	v_mfma_f32_32x32x16_bf16 v[32:47], v[230:233], v[206:209], v[32:47]
	ds_read_b128 v[230:233], v235 offset:4608
	v_add_f32_e32 v191, v191, v90
	v_add_f32_e32 v192, v192, v91
	v_cvt_pk_bf16_f32 v198, v90, v91
	v_add_f32_e32 v191, v191, v92
	v_add_f32_e32 v192, v192, v93
	v_cvt_pk_bf16_f32 v199, v92, v93
	v_mfma_f32_32x32x16_bf16 v[98:113], v[222:225], v[126:129], v[98:113]
	ds_read_b128 v[222:225], v234 offset:17504
	v_sub_f32_e32 v94, v94, v239
	v_sub_f32_e32 v95, v95, v239
	v_sub_f32_e32 v96, v96, v239
	v_sub_f32_e32 v97, v97, v239
	v_exp_f32_e32 v94, v94
	s_waitcnt lgkmcnt(5)
	v_mfma_f32_32x32x16_bf16 v[16:31], v[174:177], v[206:209], v[16:31]
	ds_read_b128 v[174:177], v235 offset:9216
	v_exp_f32_e32 v95, v95
	v_exp_f32_e32 v96, v96
	v_exp_f32_e32 v97, v97
	s_waitcnt lgkmcnt(5)
	v_mfma_f32_32x32x16_bf16 v[0:15], v[246:249], v[206:209], v[0:15]
	ds_read_b128 v[246:249], v235 offset:13824
	v_add_f32_e32 v191, v191, v94
	v_add_f32_e32 v192, v192, v95
	v_cvt_pk_bf16_f32 v200, v94, v95
	v_add_f32_e32 v191, v191, v96
	v_add_f32_e32 v192, v192, v97
	v_cvt_pk_bf16_f32 v201, v96, v97
	s_barrier
	s_cmp_lt_u32 s4, 15
	s_cbranch_scc0 .Lda_nokw
	v_add3_u32 v158, s5, v180, v182
	s_waitcnt vmcnt(3)
	ds_write_b128 v158, v[130:133] offset:0
	s_waitcnt vmcnt(2)
	ds_write_b128 v158, v[134:137] offset:8704
	s_waitcnt vmcnt(1)
	ds_write_b128 v158, v[138:141] offset:17408
	s_waitcnt vmcnt(0)
	ds_write_b128 v158, v[142:145] offset:26112
	s_lshl_b32 s18, s0, 15
	s_mov_b32 s19, 0
	v_lshl_add_u64 v[156:157], v[150:151], 0, s[18:19]
	global_load_dwordx4 v[130:133], v[156:157], off
	s_add_u32 s18, s18, 0x2000
	v_lshl_add_u64 v[156:157], v[150:151], 0, s[18:19]
	global_load_dwordx4 v[134:137], v[156:157], off
	s_add_u32 s18, s18, 0x2000
	v_lshl_add_u64 v[156:157], v[150:151], 0, s[18:19]
	global_load_dwordx4 v[138:141], v[156:157], off
	s_add_u32 s18, s18, 0x2000
	v_lshl_add_u64 v[156:157], v[150:151], 0, s[18:19]
	global_load_dwordx4 v[142:145], v[156:157], off
; __device__ void da_unit(char* lds, const Params& p, int layer, int unit) {
;     ...
;         DA_FAST_HALF(Bs, -slope2, 0)
;         if (it + 1 < NT) {
; #pragma unroll
;             for (int j = 0; j < 4; ++j) *(u32x4*)(nK + (kr_ + 32 * j) * DA_KP + kc_ * 16) = rk[j];
; #pragma unroll
;             for (int j = 0; j < 4; ++j) rk[j] = *(const u32x4*)(Vg + (size_t)tn * 16384 + j * 4096);
;         }
;         DA_FAST_HALF(Bs, -slope2, 1)
;     ...
;         if (it + 1 < NT) {
; #pragma unroll
;             for (int j = 0; j < 4; ++j) *(u32x4*)(nK + DA_KBYTES + (j >> 1) * DA_VSUB + (vr_ + 64 * (j & 1)) * DA_VP + vc_ * 16) = rk[j];
.Lda_nokw:
	v_mfma_f32_32x32x16_bf16 v[82:97], v[210:213], v[114:117], v[66:81]
	ds_read_b128 v[210:213], v234 offset:26112
	v_sub_f32_e32 v98, v98, v241
	v_sub_f32_e32 v99, v99, v241
	v_sub_f32_e32 v100, v100, v241
	v_sub_f32_e32 v101, v101, v241
	v_exp_f32_e32 v98, v98
	s_waitcnt lgkmcnt(5)
	v_mfma_f32_32x32x16_bf16 v[48:63], v[226:229], v[194:197], v[48:63]
	ds_read_b128 v[226:229], v235 offset:32
	v_exp_f32_e32 v99, v99
	v_exp_f32_e32 v100, v100
	v_exp_f32_e32 v101, v101
	s_waitcnt lgkmcnt(5)
	v_mfma_f32_32x32x16_bf16 v[32:47], v[230:233], v[194:197], v[32:47]
	ds_read_b128 v[230:233], v235 offset:4640
	v_add_f32_e32 v191, v191, v98
	v_add_f32_e32 v192, v192, v99
	v_cvt_pk_bf16_f32 v202, v98, v99
	v_add_f32_e32 v191, v191, v100
	v_add_f32_e32 v192, v192, v101
	v_cvt_pk_bf16_f32 v203, v100, v101
	v_mfma_f32_32x32x16_bf16 v[82:97], v[214:217], v[118:121], v[82:97]
	ds_read_b128 v[214:217], v234 offset:26144
	v_sub_f32_e32 v102, v102, v241
	v_sub_f32_e32 v103, v103, v241
	v_sub_f32_e32 v104, v104, v241
	v_sub_f32_e32 v105, v105, v241
	v_exp_f32_e32 v102, v102
	s_waitcnt lgkmcnt(5)
	v_mfma_f32_32x32x16_bf16 v[16:31], v[174:177], v[194:197], v[16:31]
	ds_read_b128 v[174:177], v235 offset:9248
	v_exp_f32_e32 v103, v103
	v_exp_f32_e32 v104, v104
	v_exp_f32_e32 v105, v105
	s_waitcnt lgkmcnt(5)
	v_mfma_f32_32x32x16_bf16 v[0:15], v[246:249], v[194:197], v[0:15]
	ds_read_b128 v[246:249], v235 offset:13856
	v_add_f32_e32 v191, v191, v102
	v_add_f32_e32 v192, v192, v103
	v_cvt_pk_bf16_f32 v204, v102, v103
	v_add_f32_e32 v191, v191, v104
	v_add_f32_e32 v192, v192, v105
	v_cvt_pk_bf16_f32 v205, v104, v105
	v_mfma_f32_32x32x16_bf16 v[82:97], v[218:221], v[122:125], v[82:97]
	ds_read_b128 v[218:221], v234 offset:26176
	v_sub_f32_e32 v106, v106, v241
	v_sub_f32_e32 v107, v107, v241
	v_sub_f32_e32 v108, v108, v241
	v_sub_f32_e32 v109, v109, v241
	v_exp_f32_e32 v106, v106
	s_waitcnt lgkmcnt(5)
	v_mfma_f32_32x32x16_bf16 v[48:63], v[226:229], v[198:201], v[48:63]
	ds_read_b128 v[226:229], v235 offset:64
	v_exp_f32_e32 v107, v107
	v_exp_f32_e32 v108, v108
	v_exp_f32_e32 v109, v109
	s_waitcnt lgkmcnt(5)
	v_mfma_f32_32x32x16_bf16 v[32:47], v[230:233], v[198:201], v[32:47]
	ds_read_b128 v[230:233], v235 offset:4672
	v_add_f32_e32 v191, v191, v106
	v_add_f32_e32 v192, v192, v107
	v_cvt_pk_bf16_f32 v206, v106, v107
	v_add_f32_e32 v191, v191, v108
	v_add_f32_e32 v192, v192, v109
	v_cvt_pk_bf16_f32 v207, v108, v109
	v_mfma_f32_32x32x16_bf16 v[82:97], v[222:225], v[126:129], v[82:97]
	ds_read_b128 v[222:225], v234 offset:26208
	v_sub_f32_e32 v110, v110, v241
	v_sub_f32_e32 v111, v111, v241
	v_sub_f32_e32 v112, v112, v241
	v_sub_f32_e32 v113, v113, v241
	v_exp_f32_e32 v110, v110
	s_waitcnt lgkmcnt(5)
	v_mfma_f32_32x32x16_bf16 v[16:31], v[174:177], v[198:201], v[16:31]
	ds_read_b128 v[174:177], v235 offset:9280
	v_exp_f32_e32 v111, v111
	v_exp_f32_e32 v112, v112
	v_exp_f32_e32 v113, v113
	s_waitcnt lgkmcnt(5)
	v_mfma_f32_32x32x16_bf16 v[0:15], v[246:249], v[198:201], v[0:15]
	ds_read_b128 v[246:249], v235 offset:13888
	v_add_f32_e32 v191, v191, v110
	v_add_f32_e32 v192, v192, v111
	v_cvt_pk_bf16_f32 v208, v110, v111
	v_add_f32_e32 v191, v191, v112
	v_add_f32_e32 v192, v192, v113
	v_cvt_pk_bf16_f32 v209, v112, v113
	s_or_b32 s2, s11, 64
	v_cvt_f32_u32_e32 v242, s2
	v_add_f32_e32 v242, v185, v242
	v_fma_f32 v239, v242, v250, v169
	v_fma_f32 v253, v242, -v250, v64
	v_sub_f32_e32 v241, v169, v253
	v_mfma_f32_32x32x16_bf16 v[98:113], v[210:213], v[114:117], v[66:81]
	v_sub_f32_e32 v82, v82, v239
	v_sub_f32_e32 v83, v83, v239
	v_sub_f32_e32 v84, v84, v239
	v_sub_f32_e32 v85, v85, v239
	v_exp_f32_e32 v82, v82
	s_waitcnt lgkmcnt(4)
	v_mfma_f32_32x32x16_bf16 v[48:63], v[226:229], v[202:205], v[48:63]
	ds_read_b128 v[226:229], v235 offset:96
	v_exp_f32_e32 v83, v83
	v_exp_f32_e32 v84, v84
	v_exp_f32_e32 v85, v85
	s_waitcnt lgkmcnt(4)
	v_mfma_f32_32x32x16_bf16 v[32:47], v[230:233], v[202:205], v[32:47]
	ds_read_b128 v[230:233], v235 offset:4704
	v_add_f32_e32 v191, v191, v82
	v_add_f32_e32 v192, v192, v83
	v_cvt_pk_bf16_f32 v194, v82, v83
	v_add_f32_e32 v191, v191, v84
	v_add_f32_e32 v192, v192, v85
	v_cvt_pk_bf16_f32 v195, v84, v85
	v_mfma_f32_32x32x16_bf16 v[98:113], v[214:217], v[118:121], v[98:113]
	v_sub_f32_e32 v86, v86, v239
	v_sub_f32_e32 v87, v87, v239
	v_sub_f32_e32 v88, v88, v239
	v_sub_f32_e32 v89, v89, v239
	v_exp_f32_e32 v86, v86
	s_waitcnt lgkmcnt(3)
	v_mfma_f32_32x32x16_bf16 v[16:31], v[174:177], v[202:205], v[16:31]
	ds_read_b128 v[174:177], v235 offset:9312
	v_exp_f32_e32 v87, v87
	v_exp_f32_e32 v88, v88
	v_exp_f32_e32 v89, v89
	s_waitcnt lgkmcnt(3)
	v_mfma_f32_32x32x16_bf16 v[0:15], v[246:249], v[202:205], v[0:15]
	ds_read_b128 v[246:249], v235 offset:13920
	v_add_f32_e32 v191, v191, v86
	v_add_f32_e32 v192, v192, v87
	v_cvt_pk_bf16_f32 v196, v86, v87
	v_add_f32_e32 v191, v191, v88
	v_add_f32_e32 v192, v192, v89
	v_cvt_pk_bf16_f32 v197, v88, v89
	v_mfma_f32_32x32x16_bf16 v[98:113], v[218:221], v[122:125], v[98:113]
	v_sub_f32_e32 v90, v90, v239
	v_sub_f32_e32 v91, v91, v239
	v_sub_f32_e32 v92, v92, v239
	v_sub_f32_e32 v93, v93, v239
	v_exp_f32_e32 v90, v90
	s_waitcnt lgkmcnt(3)
	v_mfma_f32_32x32x16_bf16 v[48:63], v[226:229], v[206:209], v[48:63]
	ds_read_b128 v[226:229], v235 offset:18432
	v_exp_f32_e32 v91, v91
	v_exp_f32_e32 v92, v92
	v_exp_f32_e32 v93, v93
	s_waitcnt lgkmcnt(3)
	v_mfma_f32_32x32x16_bf16 v[32:47], v[230:233], v[206:209], v[32:47]
	ds_read_b128 v[230:233], v235 offset:23040
	v_add_f32_e32 v191, v191, v90
	v_add_f32_e32 v192, v192, v91
	v_cvt_pk_bf16_f32 v198, v90, v91
	v_add_f32_e32 v191, v191, v92
	v_add_f32_e32 v192, v192, v93
	v_cvt_pk_bf16_f32 v199, v92, v93
	v_mfma_f32_32x32x16_bf16 v[98:113], v[222:225], v[126:129], v[98:113]
	v_sub_f32_e32 v94, v94, v239
	v_sub_f32_e32 v95, v95, v239
	v_sub_f32_e32 v96, v96, v239
	v_sub_f32_e32 v97, v97, v239
	v_exp_f32_e32 v94, v94
	s_waitcnt lgkmcnt(3)
	v_mfma_f32_32x32x16_bf16 v[16:31], v[174:177], v[206:209], v[16:31]
	ds_read_b128 v[174:177], v235 offset:27648
	v_exp_f32_e32 v95, v95
	v_exp_f32_e32 v96, v96
	v_exp_f32_e32 v97, v97
	s_waitcnt lgkmcnt(3)
	v_mfma_f32_32x32x16_bf16 v[0:15], v[246:249], v[206:209], v[0:15]
	ds_read_b128 v[246:249], v235 offset:32256
	v_add_f32_e32 v191, v191, v94
	v_add_f32_e32 v192, v192, v95
	v_cvt_pk_bf16_f32 v200, v94, v95
	v_add_f32_e32 v191, v191, v96
	v_add_f32_e32 v192, v192, v97
	v_cvt_pk_bf16_f32 v201, v96, v97
	s_cmp_lt_u32 s4, 15
	s_cbranch_scc0 .Lda_novw
	v_add3_u32 v158, s5, v183, v181
	s_waitcnt vmcnt(3)
	ds_write_b128 v158, v[130:133] offset:34816
	s_waitcnt vmcnt(2)
	ds_write_b128 v158, v[134:137] offset:44032
	s_waitcnt vmcnt(1)
	ds_write_b128 v158, v[138:141] offset:53248
	s_waitcnt vmcnt(0)
	ds_write_b128 v158, v[142:145] offset:62464

; __device__ void da_unit(char* lds, const Params& p, int layer, int unit) {
;     ...
;         DA_FAST_HALF(Bs, -slope2, 0)
;         if (it + 1 < NT) {
; #pragma unroll
;             for (int j = 0; j < 4; ++j) *(u32x4*)(nK + (kr_ + 32 * j) * DA_KP + kc_ * 16) = rk[j];
; #pragma unroll
;             for (int j = 0; j < 4; ++j) rk[j] = *(const u32x4*)(Vg + (size_t)tn * 16384 + j * 4096);
;         }
;         DA_FAST_HALF(Bs, -slope2, 1)
;     ...
;         if (it + 1 < NT) {
; #pragma unroll
;             for (int j = 0; j < 4; ++j) *(u32x4*)(nK + DA_KBYTES + (j >> 1) * DA_VSUB + (vr_ + 64 * (j & 1)) * DA_VP + vc_ * 16) = rk[j];
;         }
;         __syncthreads();
;     }
.Lda_nocflip:
	ds_read_b128 v[210:213], v236 offset:0
	ds_read_b128 v[214:217], v236 offset:32
	ds_read_b128 v[218:221], v236 offset:64
	ds_read_b128 v[222:225], v236 offset:96
	v_mfma_f32_32x32x16_bf16 v[48:63], v[226:229], v[194:197], v[48:63]
	ds_read_b128 v[226:229], v235 offset:18464
	v_sub_f32_e32 v98, v98, v241
	v_sub_f32_e32 v99, v99, v241
	v_sub_f32_e32 v100, v100, v241
	v_sub_f32_e32 v101, v101, v241
	v_exp_f32_e32 v98, v98
	v_mfma_f32_32x32x16_bf16 v[32:47], v[230:233], v[194:197], v[32:47]
	ds_read_b128 v[230:233], v235 offset:23072
	v_exp_f32_e32 v99, v99
	v_exp_f32_e32 v100, v100
	v_exp_f32_e32 v101, v101
	s_waitcnt lgkmcnt(5)
	v_mfma_f32_32x32x16_bf16 v[82:97], v[210:213], v[114:117], v[66:81]
	ds_read_b128 v[210:213], v236 offset:8704
	v_add_f32_e32 v191, v191, v98
	v_add_f32_e32 v192, v192, v99
	v_cvt_pk_bf16_f32 v202, v98, v99
	v_add_f32_e32 v191, v191, v100
	v_add_f32_e32 v192, v192, v101
	v_cvt_pk_bf16_f32 v203, v100, v101
	v_mfma_f32_32x32x16_bf16 v[16:31], v[174:177], v[194:197], v[16:31]
	ds_read_b128 v[174:177], v235 offset:27680
	v_sub_f32_e32 v102, v102, v241
	v_sub_f32_e32 v103, v103, v241
	v_sub_f32_e32 v104, v104, v241
	v_sub_f32_e32 v105, v105, v241
	v_exp_f32_e32 v102, v102
	v_mfma_f32_32x32x16_bf16 v[0:15], v[246:249], v[194:197], v[0:15]
	ds_read_b128 v[246:249], v235 offset:32288
	v_exp_f32_e32 v103, v103
	v_exp_f32_e32 v104, v104
	v_exp_f32_e32 v105, v105
	s_waitcnt lgkmcnt(7)
	v_mfma_f32_32x32x16_bf16 v[82:97], v[214:217], v[118:121], v[82:97]
	ds_read_b128 v[214:217], v236 offset:8736
	v_add_f32_e32 v191, v191, v102
	v_add_f32_e32 v192, v192, v103
	v_cvt_pk_bf16_f32 v204, v102, v103
	v_add_f32_e32 v191, v191, v104
	v_add_f32_e32 v192, v192, v105
	v_cvt_pk_bf16_f32 v205, v104, v105
	s_waitcnt lgkmcnt(5)
	v_mfma_f32_32x32x16_bf16 v[48:63], v[226:229], v[198:201], v[48:63]
	ds_read_b128 v[226:229], v235 offset:18496
	v_sub_f32_e32 v106, v106, v241
	v_sub_f32_e32 v107, v107, v241
	v_sub_f32_e32 v108, v108, v241
	v_sub_f32_e32 v109, v109, v241
	v_exp_f32_e32 v106, v106
	s_waitcnt lgkmcnt(5)
	v_mfma_f32_32x32x16_bf16 v[32:47], v[230:233], v[198:201], v[32:47]
	ds_read_b128 v[230:233], v235 offset:23104
	v_exp_f32_e32 v107, v107
	v_exp_f32_e32 v108, v108
	v_exp_f32_e32 v109, v109
	v_mfma_f32_32x32x16_bf16 v[82:97], v[218:221], v[122:125], v[82:97]
	ds_read_b128 v[218:221], v236 offset:8768
	v_add_f32_e32 v191, v191, v106
	v_add_f32_e32 v192, v192, v107
	v_cvt_pk_bf16_f32 v206, v106, v107
	v_add_f32_e32 v191, v191, v108
	v_add_f32_e32 v192, v192, v109
	v_cvt_pk_bf16_f32 v207, v108, v109
	s_waitcnt lgkmcnt(5)
	v_mfma_f32_32x32x16_bf16 v[16:31], v[174:177], v[198:201], v[16:31]
	ds_read_b128 v[174:177], v235 offset:27712
	v_sub_f32_e32 v110, v110, v241
	v_sub_f32_e32 v111, v111, v241
	v_sub_f32_e32 v112, v112, v241
	v_sub_f32_e32 v113, v113, v241
	v_exp_f32_e32 v110, v110
	s_waitcnt lgkmcnt(5)
	v_mfma_f32_32x32x16_bf16 v[0:15], v[246:249], v[198:201], v[0:15]
	ds_read_b128 v[246:249], v235 offset:32320
	v_exp_f32_e32 v111, v111
	v_exp_f32_e32 v112, v112
	v_exp_f32_e32 v113, v113
	v_mfma_f32_32x32x16_bf16 v[82:97], v[222:225], v[126:129], v[82:97]
	ds_read_b128 v[222:225], v236 offset:8800
	v_add_f32_e32 v191, v191, v110
	v_add_f32_e32 v192, v192, v111
	v_cvt_pk_bf16_f32 v208, v110, v111
	v_add_f32_e32 v191, v191, v112
	v_add_f32_e32 v192, v192, v113
	v_cvt_pk_bf16_f32 v209, v112, v113
	s_add_i32 s4, s4, 1
	s_cmp_lt_u32 s4, 16
	s_cbranch_scc1 .Lda_top
	s_waitcnt lgkmcnt(5)
	v_mfma_f32_32x32x16_bf16 v[48:63], v[226:229], v[202:205], v[48:63]
	ds_read_b128 v[226:229], v235 offset:18528
	s_waitcnt lgkmcnt(5)
	v_mfma_f32_32x32x16_bf16 v[32:47], v[230:233], v[202:205], v[32:47]
	ds_read_b128 v[230:233], v235 offset:23136
	s_waitcnt lgkmcnt(4)
	v_mfma_f32_32x32x16_bf16 v[16:31], v[174:177], v[202:205], v[16:31]
	ds_read_b128 v[174:177], v235 offset:27744
	s_waitcnt lgkmcnt(4)
	v_mfma_f32_32x32x16_bf16 v[0:15], v[246:249], v[202:205], v[0:15]
	ds_read_b128 v[246:249], v235 offset:32352
	s_waitcnt lgkmcnt(3)
	v_mfma_f32_32x32x16_bf16 v[48:63], v[226:229], v[206:209], v[48:63]
	s_waitcnt lgkmcnt(2)
	v_mfma_f32_32x32x16_bf16 v[32:47], v[230:233], v[206:209], v[32:47]
	s_waitcnt lgkmcnt(1)
	v_mfma_f32_32x32x16_bf16 v[16:31], v[174:177], v[206:209], v[16:31]
	s_waitcnt lgkmcnt(0)
	v_mfma_f32_32x32x16_bf16 v[0:15], v[246:249], v[206:209], v[0:15]
	v_add_f32_e32 v191, v191, v192
	s_nop 7
	s_nop 3
	v_add_f32_e32 v193, v193, v191
